# GEMM_IN: each workgroup starts its k loop at a different k-tile (wraps around), so concurrent tiles do not hit the same L2 lines and channels at the same time
# speedup vs baseline: 1.4102x; 1.0244x over previous
.LBB0_271:
	v_and_b32_e32 v150, 63, v128
	v_lshrrev_b32_e32 v151, 6, v128
	v_lshrrev_b32_e32 v152, 3, v150
	v_readfirstlane_b32 s0, v151
	v_and_b32_e32 v153, 7, v150
	v_xor_b32_e32 v153, v153, v152
	v_lshlrev_b32_e32 v153, 4, v153
	v_lshl_add_u32 v153, v152, 11, v153
	s_lshl_b32 s1, s0, 16
	v_add_u32_e32 v132, s1, v153
	v_add_u32_e32 v133, 0x3c00, v132
	v_add_u32_e32 v134, 0x7800, v132
	v_add_u32_e32 v135, 0xb400, v132
	s_lshl_b32 s1, s0, 12
	s_add_u32 s5, s1, 0
	s_add_u32 s6, s1, 16384
	s_add_u32 s7, s1, 45056
	s_add_u32 s8, s1, 61440
	v_and_b32_e32 v152, 15, v150
	v_lshrrev_b32_e32 v153, 4, v150
	v_and_b32_e32 v154, 7, v152
	v_xor_b32_e32 v154, v154, v153
	v_lshlrev_b32_e32 v154, 4, v154
	v_lshl_add_u32 v154, v152, 7, v154
	s_lshr_b32 s1, s0, 1
	s_lshl_b32 s1, s1, 13
	v_add_u32_e32 v136, s1, v154
	v_xor_b32_e32 v137, 64, v136
	v_add_u32_e32 v138, 0xb000, v136
	v_add_u32_e32 v139, 0xb000, v137
	s_and_b32 s1, s0, 1
	s_lshl_b32 s1, s1, 13
	s_add_u32 s1, s1, 16384
	v_add_u32_e32 v140, s1, v154
	v_xor_b32_e32 v141, 64, v140
	v_add_u32_e32 v142, 0xb000, v140
	v_add_u32_e32 v143, 0xb000, v141
	s_and_b32 s1, s0, 1
	s_lshl_b32 s1, s1, 6
	v_add_u32_e32 v152, s1, v152
	v_mov_b32_e32 v154, 0x4a00
	v_mul_lo_u32 v152, v152, v154
	v_lshlrev_b32_e32 v153, 3, v153
	s_lshr_b32 s1, s0, 1
	s_lshl_b32 s1, s1, 7
	v_add3_u32 v146, v152, v153, s1
	v_add_u32_e32 v147, 0x4a000, v146
	v_add_u32_e32 v148, 0x94000, v146
	v_add_u32_e32 v149, 0xde000, v146
	v_readlane_b32 s25, v252, 0
	v_readlane_b32 s98, v252, 0
	s_lshr_b32 s98, s98, 3
	s_and_b32 s98, s98, 15
	s_and_b32 s0, s25, 63
	s_lshr_b32 s1, s25, 6
	s_mul_i32 s4, s70, 0x1280000
	s_lshl_b32 s39, s1, 18
	s_add_u32 s4, s4, s39
	s_add_u32 s26, s96, s4
	s_addc_u32 s27, s97, 0
	s_lshl_b32 s4, s0, 18
	s_add_u32 s4, s4, 0x82a6100
	s_add_u32 s28, s96, s4
	s_addc_u32 s29, s97, 0
	s_lshl_b32 s0, s98, 7
	s_add_u32 s26, s26, s0
	s_addc_u32 s27, s27, 0
	s_add_u32 s28, s28, s0
	s_addc_u32 s29, s29, 0
	s_mov_b32 s99, s98
	s_mov_b32 m0, s5
	s_nop 0
	global_load_lds_dwordx4 v132, s[26:27] offset:0
	global_load_lds_dwordx4 v133, s[26:27] offset:1024
	global_load_lds_dwordx4 v134, s[26:27] offset:2048
	global_load_lds_dwordx4 v135, s[26:27] offset:3072
	s_mov_b32 m0, s6
	s_nop 0
	global_load_lds_dwordx4 v132, s[28:29] offset:0
	global_load_lds_dwordx4 v133, s[28:29] offset:1024
	global_load_lds_dwordx4 v134, s[28:29] offset:2048
	global_load_lds_dwordx4 v135, s[28:29] offset:3072
	s_waitcnt vmcnt(0)
.Lgin_tile:
	s_waitcnt vmcnt(16)
	s_barrier
	s_add_i32 s99, s99, 1
	s_cmp_eq_u32 s99, 16
	s_movk_i32 s0, 0x80
	s_cselect_b32 s0, 0xfffff880, s0
	s_cselect_b32 s99, 0, s99
	s_ashr_i32 s1, s0, 31
	s_add_u32 s26, s26, s0
	s_addc_u32 s27, s27, s1
	s_add_u32 s28, s28, s0
	s_addc_u32 s29, s29, s1
	s_mov_b32 m0, s7
	s_nop 0
	global_load_lds_dwordx4 v132, s[26:27] offset:0
	global_load_lds_dwordx4 v133, s[26:27] offset:1024
	global_load_lds_dwordx4 v134, s[26:27] offset:2048
	global_load_lds_dwordx4 v135, s[26:27] offset:3072
	s_mov_b32 m0, s8
	s_nop 0
	global_load_lds_dwordx4 v132, s[28:29] offset:0
	global_load_lds_dwordx4 v133, s[28:29] offset:1024
	global_load_lds_dwordx4 v134, s[28:29] offset:2048
	global_load_lds_dwordx4 v135, s[28:29] offset:3072
	ds_read_b128 v[64:67], v136 offset:0
	ds_read_b128 v[96:99], v140 offset:0
	ds_read_b128 v[100:103], v140 offset:2048
	ds_read_b128 v[104:107], v140 offset:4096
	ds_read_b128 v[108:111], v140 offset:6144
	ds_read_b128 v[68:71], v136 offset:2048
	ds_read_b128 v[72:75], v136 offset:4096
	ds_read_b128 v[76:79], v136 offset:6144
	s_waitcnt lgkmcnt(3)
	v_mfma_f32_16x16x32_bf16 v[0:3], v[64:67], v[96:99], 0
	v_mfma_f32_16x16x32_bf16 v[4:7], v[64:67], v[100:103], 0
	ds_read_b128 v[80:83], v137 offset:0
	v_mfma_f32_16x16x32_bf16 v[8:11], v[64:67], v[104:107], 0
	v_mfma_f32_16x16x32_bf16 v[12:15], v[64:67], v[108:111], 0
	ds_read_b128 v[112:115], v141 offset:0
	s_waitcnt lgkmcnt(4)
	v_mfma_f32_16x16x32_bf16 v[16:19], v[68:71], v[96:99], 0
	v_mfma_f32_16x16x32_bf16 v[20:23], v[68:71], v[100:103], 0
	ds_read_b128 v[116:119], v141 offset:2048
	v_mfma_f32_16x16x32_bf16 v[24:27], v[68:71], v[104:107], 0
	v_mfma_f32_16x16x32_bf16 v[28:31], v[68:71], v[108:111], 0
	ds_read_b128 v[120:123], v141 offset:4096
	s_waitcnt lgkmcnt(5)
	v_mfma_f32_16x16x32_bf16 v[32:35], v[72:75], v[96:99], 0
	v_mfma_f32_16x16x32_bf16 v[36:39], v[72:75], v[100:103], 0
	ds_read_b128 v[124:127], v141 offset:6144
	v_mfma_f32_16x16x32_bf16 v[40:43], v[72:75], v[104:107], 0
	v_mfma_f32_16x16x32_bf16 v[44:47], v[72:75], v[108:111], 0
	ds_read_b128 v[84:87], v137 offset:2048
	s_waitcnt lgkmcnt(6)
	v_mfma_f32_16x16x32_bf16 v[48:51], v[76:79], v[96:99], 0
	v_mfma_f32_16x16x32_bf16 v[52:55], v[76:79], v[100:103], 0
	ds_read_b128 v[88:91], v137 offset:4096
	v_mfma_f32_16x16x32_bf16 v[56:59], v[76:79], v[104:107], 0
	v_mfma_f32_16x16x32_bf16 v[60:63], v[76:79], v[108:111], 0
	ds_read_b128 v[92:95], v137 offset:6144
	s_waitcnt lgkmcnt(3)
	v_mfma_f32_16x16x32_bf16 v[0:3], v[80:83], v[112:115], v[0:3]
	v_mfma_f32_16x16x32_bf16 v[4:7], v[80:83], v[116:119], v[4:7]
	v_mfma_f32_16x16x32_bf16 v[8:11], v[80:83], v[120:123], v[8:11]
	v_mfma_f32_16x16x32_bf16 v[12:15], v[80:83], v[124:127], v[12:15]
	s_waitcnt lgkmcnt(2)
	v_mfma_f32_16x16x32_bf16 v[16:19], v[84:87], v[112:115], v[16:19]
	v_mfma_f32_16x16x32_bf16 v[20:23], v[84:87], v[116:119], v[20:23]
	v_mfma_f32_16x16x32_bf16 v[24:27], v[84:87], v[120:123], v[24:27]
	v_mfma_f32_16x16x32_bf16 v[28:31], v[84:87], v[124:127], v[28:31]
	s_waitcnt lgkmcnt(1)
	v_mfma_f32_16x16x32_bf16 v[32:35], v[88:91], v[112:115], v[32:35]
	v_mfma_f32_16x16x32_bf16 v[36:39], v[88:91], v[116:119], v[36:39]
	v_mfma_f32_16x16x32_bf16 v[40:43], v[88:91], v[120:123], v[40:43]
	v_mfma_f32_16x16x32_bf16 v[44:47], v[88:91], v[124:127], v[44:47]
	s_waitcnt lgkmcnt(0)
	v_mfma_f32_16x16x32_bf16 v[48:51], v[92:95], v[112:115], v[48:51]
	v_mfma_f32_16x16x32_bf16 v[52:55], v[92:95], v[116:119], v[52:55]
	v_mfma_f32_16x16x32_bf16 v[56:59], v[92:95], v[120:123], v[56:59]
	v_mfma_f32_16x16x32_bf16 v[60:63], v[92:95], v[124:127], v[60:63]
	s_waitcnt vmcnt(0)
	s_barrier
	s_add_i32 s99, s99, 1
	s_cmp_eq_u32 s99, 16
	s_movk_i32 s0, 0x80
	s_cselect_b32 s0, 0xfffff880, s0
	s_cselect_b32 s99, 0, s99
	s_ashr_i32 s1, s0, 31
	s_add_u32 s26, s26, s0
	s_addc_u32 s27, s27, s1
	s_add_u32 s28, s28, s0
	s_addc_u32 s29, s29, s1
	s_mov_b32 m0, s5
	s_nop 0
	global_load_lds_dwordx4 v132, s[26:27] offset:0
	global_load_lds_dwordx4 v133, s[26:27] offset:1024
	global_load_lds_dwordx4 v134, s[26:27] offset:2048
	global_load_lds_dwordx4 v135, s[26:27] offset:3072
	s_mov_b32 m0, s6
	s_nop 0
	global_load_lds_dwordx4 v132, s[28:29] offset:0
	global_load_lds_dwordx4 v133, s[28:29] offset:1024
	global_load_lds_dwordx4 v134, s[28:29] offset:2048
	global_load_lds_dwordx4 v135, s[28:29] offset:3072
	ds_read_b128 v[64:67], v138 offset:0
	ds_read_b128 v[96:99], v142 offset:0
	ds_read_b128 v[100:103], v142 offset:2048
	ds_read_b128 v[104:107], v142 offset:4096
	ds_read_b128 v[108:111], v142 offset:6144
	ds_read_b128 v[68:71], v138 offset:2048
	ds_read_b128 v[72:75], v138 offset:4096
	ds_read_b128 v[76:79], v138 offset:6144
	s_waitcnt lgkmcnt(3)
	v_mfma_f32_16x16x32_bf16 v[0:3], v[64:67], v[96:99], v[0:3]
	v_mfma_f32_16x16x32_bf16 v[4:7], v[64:67], v[100:103], v[4:7]
	ds_read_b128 v[80:83], v139 offset:0
	v_mfma_f32_16x16x32_bf16 v[8:11], v[64:67], v[104:107], v[8:11]
	v_mfma_f32_16x16x32_bf16 v[12:15], v[64:67], v[108:111], v[12:15]
	ds_read_b128 v[112:115], v143 offset:0
	s_waitcnt lgkmcnt(4)
	v_mfma_f32_16x16x32_bf16 v[16:19], v[68:71], v[96:99], v[16:19]
	v_mfma_f32_16x16x32_bf16 v[20:23], v[68:71], v[100:103], v[20:23]
	ds_read_b128 v[116:119], v143 offset:2048
	v_mfma_f32_16x16x32_bf16 v[24:27], v[68:71], v[104:107], v[24:27]
	v_mfma_f32_16x16x32_bf16 v[28:31], v[68:71], v[108:111], v[28:31]
	ds_read_b128 v[120:123], v143 offset:4096
	s_waitcnt lgkmcnt(5)
	v_mfma_f32_16x16x32_bf16 v[32:35], v[72:75], v[96:99], v[32:35]
	v_mfma_f32_16x16x32_bf16 v[36:39], v[72:75], v[100:103], v[36:39]
	ds_read_b128 v[124:127], v143 offset:6144
	v_mfma_f32_16x16x32_bf16 v[40:43], v[72:75], v[104:107], v[40:43]
	v_mfma_f32_16x16x32_bf16 v[44:47], v[72:75], v[108:111], v[44:47]
	ds_read_b128 v[84:87], v139 offset:2048
	s_waitcnt lgkmcnt(6)
	v_mfma_f32_16x16x32_bf16 v[48:51], v[76:79], v[96:99], v[48:51]
	v_mfma_f32_16x16x32_bf16 v[52:55], v[76:79], v[100:103], v[52:55]
	ds_read_b128 v[88:91], v139 offset:4096
	v_mfma_f32_16x16x32_bf16 v[56:59], v[76:79], v[104:107], v[56:59]
	v_mfma_f32_16x16x32_bf16 v[60:63], v[76:79], v[108:111], v[60:63]
	ds_read_b128 v[92:95], v139 offset:6144
	s_waitcnt lgkmcnt(3)
	v_mfma_f32_16x16x32_bf16 v[0:3], v[80:83], v[112:115], v[0:3]
	v_mfma_f32_16x16x32_bf16 v[4:7], v[80:83], v[116:119], v[4:7]
	v_mfma_f32_16x16x32_bf16 v[8:11], v[80:83], v[120:123], v[8:11]
	v_mfma_f32_16x16x32_bf16 v[12:15], v[80:83], v[124:127], v[12:15]
	s_waitcnt lgkmcnt(2)
	v_mfma_f32_16x16x32_bf16 v[16:19], v[84:87], v[112:115], v[16:19]
	v_mfma_f32_16x16x32_bf16 v[20:23], v[84:87], v[116:119], v[20:23]
	v_mfma_f32_16x16x32_bf16 v[24:27], v[84:87], v[120:123], v[24:27]
	v_mfma_f32_16x16x32_bf16 v[28:31], v[84:87], v[124:127], v[28:31]
	s_waitcnt lgkmcnt(1)
	v_mfma_f32_16x16x32_bf16 v[32:35], v[88:91], v[112:115], v[32:35]
	v_mfma_f32_16x16x32_bf16 v[36:39], v[88:91], v[116:119], v[36:39]
	v_mfma_f32_16x16x32_bf16 v[40:43], v[88:91], v[120:123], v[40:43]
	v_mfma_f32_16x16x32_bf16 v[44:47], v[88:91], v[124:127], v[44:47]
	s_waitcnt lgkmcnt(0)
	v_mfma_f32_16x16x32_bf16 v[48:51], v[92:95], v[112:115], v[48:51]
	v_mfma_f32_16x16x32_bf16 v[52:55], v[92:95], v[116:119], v[52:55]
	v_mfma_f32_16x16x32_bf16 v[56:59], v[92:95], v[120:123], v[56:59]
	v_mfma_f32_16x16x32_bf16 v[60:63], v[92:95], v[124:127], v[60:63]
	s_waitcnt vmcnt(0)
	s_barrier
	s_add_i32 s99, s99, 1
	s_cmp_eq_u32 s99, 16
	s_movk_i32 s0, 0x80
	s_cselect_b32 s0, 0xfffff880, s0
	s_cselect_b32 s99, 0, s99
	s_ashr_i32 s1, s0, 31
	s_add_u32 s26, s26, s0
	s_addc_u32 s27, s27, s1
	s_add_u32 s28, s28, s0
	s_addc_u32 s29, s29, s1
	s_mov_b32 m0, s7
	s_nop 0
	global_load_lds_dwordx4 v132, s[26:27] offset:0
	global_load_lds_dwordx4 v133, s[26:27] offset:1024
	global_load_lds_dwordx4 v134, s[26:27] offset:2048
	global_load_lds_dwordx4 v135, s[26:27] offset:3072
	s_mov_b32 m0, s8
	s_nop 0
	global_load_lds_dwordx4 v132, s[28:29] offset:0
	global_load_lds_dwordx4 v133, s[28:29] offset:1024
	global_load_lds_dwordx4 v134, s[28:29] offset:2048
	global_load_lds_dwordx4 v135, s[28:29] offset:3072
	ds_read_b128 v[64:67], v136 offset:0
	ds_read_b128 v[96:99], v140 offset:0
	ds_read_b128 v[100:103], v140 offset:2048
	ds_read_b128 v[104:107], v140 offset:4096
	ds_read_b128 v[108:111], v140 offset:6144
	ds_read_b128 v[68:71], v136 offset:2048
	ds_read_b128 v[72:75], v136 offset:4096
	ds_read_b128 v[76:79], v136 offset:6144
	s_waitcnt lgkmcnt(3)
	v_mfma_f32_16x16x32_bf16 v[0:3], v[64:67], v[96:99], v[0:3]
	v_mfma_f32_16x16x32_bf16 v[4:7], v[64:67], v[100:103], v[4:7]
	ds_read_b128 v[80:83], v137 offset:0
	v_mfma_f32_16x16x32_bf16 v[8:11], v[64:67], v[104:107], v[8:11]
	v_mfma_f32_16x16x32_bf16 v[12:15], v[64:67], v[108:111], v[12:15]
	ds_read_b128 v[112:115], v141 offset:0
	s_waitcnt lgkmcnt(4)
	v_mfma_f32_16x16x32_bf16 v[16:19], v[68:71], v[96:99], v[16:19]
	v_mfma_f32_16x16x32_bf16 v[20:23], v[68:71], v[100:103], v[20:23]
	ds_read_b128 v[116:119], v141 offset:2048
	v_mfma_f32_16x16x32_bf16 v[24:27], v[68:71], v[104:107], v[24:27]
	v_mfma_f32_16x16x32_bf16 v[28:31], v[68:71], v[108:111], v[28:31]
	ds_read_b128 v[120:123], v141 offset:4096
	s_waitcnt lgkmcnt(5)
	v_mfma_f32_16x16x32_bf16 v[32:35], v[72:75], v[96:99], v[32:35]
	v_mfma_f32_16x16x32_bf16 v[36:39], v[72:75], v[100:103], v[36:39]
	ds_read_b128 v[124:127], v141 offset:6144
	v_mfma_f32_16x16x32_bf16 v[40:43], v[72:75], v[104:107], v[40:43]
	v_mfma_f32_16x16x32_bf16 v[44:47], v[72:75], v[108:111], v[44:47]
	ds_read_b128 v[84:87], v137 offset:2048
	s_waitcnt lgkmcnt(6)
	v_mfma_f32_16x16x32_bf16 v[48:51], v[76:79], v[96:99], v[48:51]
	v_mfma_f32_16x16x32_bf16 v[52:55], v[76:79], v[100:103], v[52:55]
	ds_read_b128 v[88:91], v137 offset:4096
	v_mfma_f32_16x16x32_bf16 v[56:59], v[76:79], v[104:107], v[56:59]
	v_mfma_f32_16x16x32_bf16 v[60:63], v[76:79], v[108:111], v[60:63]
	ds_read_b128 v[92:95], v137 offset:6144
	s_waitcnt lgkmcnt(3)
	v_mfma_f32_16x16x32_bf16 v[0:3], v[80:83], v[112:115], v[0:3]
	v_mfma_f32_16x16x32_bf16 v[4:7], v[80:83], v[116:119], v[4:7]
	v_mfma_f32_16x16x32_bf16 v[8:11], v[80:83], v[120:123], v[8:11]
	v_mfma_f32_16x16x32_bf16 v[12:15], v[80:83], v[124:127], v[12:15]
	s_waitcnt lgkmcnt(2)
	v_mfma_f32_16x16x32_bf16 v[16:19], v[84:87], v[112:115], v[16:19]
	v_mfma_f32_16x16x32_bf16 v[20:23], v[84:87], v[116:119], v[20:23]
	v_mfma_f32_16x16x32_bf16 v[24:27], v[84:87], v[120:123], v[24:27]
	v_mfma_f32_16x16x32_bf16 v[28:31], v[84:87], v[124:127], v[28:31]
	s_waitcnt lgkmcnt(1)
	v_mfma_f32_16x16x32_bf16 v[32:35], v[88:91], v[112:115], v[32:35]
	v_mfma_f32_16x16x32_bf16 v[36:39], v[88:91], v[116:119], v[36:39]
	v_mfma_f32_16x16x32_bf16 v[40:43], v[88:91], v[120:123], v[40:43]
	v_mfma_f32_16x16x32_bf16 v[44:47], v[88:91], v[124:127], v[44:47]
	s_waitcnt lgkmcnt(0)
	v_mfma_f32_16x16x32_bf16 v[48:51], v[92:95], v[112:115], v[48:51]
	v_mfma_f32_16x16x32_bf16 v[52:55], v[92:95], v[116:119], v[52:55]
	v_mfma_f32_16x16x32_bf16 v[56:59], v[92:95], v[120:123], v[56:59]
	v_mfma_f32_16x16x32_bf16 v[60:63], v[92:95], v[124:127], v[60:63]
	s_waitcnt vmcnt(0)
	s_barrier
	s_add_i32 s99, s99, 1
	s_cmp_eq_u32 s99, 16
	s_movk_i32 s0, 0x80
	s_cselect_b32 s0, 0xfffff880, s0
	s_cselect_b32 s99, 0, s99
	s_ashr_i32 s1, s0, 31
	s_add_u32 s26, s26, s0
	s_addc_u32 s27, s27, s1
	s_add_u32 s28, s28, s0
	s_addc_u32 s29, s29, s1
	s_mov_b32 m0, s5
	s_nop 0
	global_load_lds_dwordx4 v132, s[26:27] offset:0
	global_load_lds_dwordx4 v133, s[26:27] offset:1024
	global_load_lds_dwordx4 v134, s[26:27] offset:2048
	global_load_lds_dwordx4 v135, s[26:27] offset:3072
	s_mov_b32 m0, s6
	s_nop 0
	global_load_lds_dwordx4 v132, s[28:29] offset:0
	global_load_lds_dwordx4 v133, s[28:29] offset:1024
	global_load_lds_dwordx4 v134, s[28:29] offset:2048
	global_load_lds_dwordx4 v135, s[28:29] offset:3072
	ds_read_b128 v[64:67], v138 offset:0
	ds_read_b128 v[96:99], v142 offset:0
	ds_read_b128 v[100:103], v142 offset:2048
	ds_read_b128 v[104:107], v142 offset:4096
	ds_read_b128 v[108:111], v142 offset:6144
	ds_read_b128 v[68:71], v138 offset:2048
	ds_read_b128 v[72:75], v138 offset:4096
	ds_read_b128 v[76:79], v138 offset:6144
	s_waitcnt lgkmcnt(3)
	v_mfma_f32_16x16x32_bf16 v[0:3], v[64:67], v[96:99], v[0:3]
	v_mfma_f32_16x16x32_bf16 v[4:7], v[64:67], v[100:103], v[4:7]
	ds_read_b128 v[80:83], v139 offset:0
	v_mfma_f32_16x16x32_bf16 v[8:11], v[64:67], v[104:107], v[8:11]
	v_mfma_f32_16x16x32_bf16 v[12:15], v[64:67], v[108:111], v[12:15]
	ds_read_b128 v[112:115], v143 offset:0
	s_waitcnt lgkmcnt(4)
	v_mfma_f32_16x16x32_bf16 v[16:19], v[68:71], v[96:99], v[16:19]
	v_mfma_f32_16x16x32_bf16 v[20:23], v[68:71], v[100:103], v[20:23]
	ds_read_b128 v[116:119], v143 offset:2048
	v_mfma_f32_16x16x32_bf16 v[24:27], v[68:71], v[104:107], v[24:27]
	v_mfma_f32_16x16x32_bf16 v[28:31], v[68:71], v[108:111], v[28:31]
	ds_read_b128 v[120:123], v143 offset:4096
	s_waitcnt lgkmcnt(5)
	v_mfma_f32_16x16x32_bf16 v[32:35], v[72:75], v[96:99], v[32:35]
	v_mfma_f32_16x16x32_bf16 v[36:39], v[72:75], v[100:103], v[36:39]
	ds_read_b128 v[124:127], v143 offset:6144
	v_mfma_f32_16x16x32_bf16 v[40:43], v[72:75], v[104:107], v[40:43]
	v_mfma_f32_16x16x32_bf16 v[44:47], v[72:75], v[108:111], v[44:47]
	ds_read_b128 v[84:87], v139 offset:2048
	s_waitcnt lgkmcnt(6)
	v_mfma_f32_16x16x32_bf16 v[48:51], v[76:79], v[96:99], v[48:51]
	v_mfma_f32_16x16x32_bf16 v[52:55], v[76:79], v[100:103], v[52:55]
	ds_read_b128 v[88:91], v139 offset:4096
	v_mfma_f32_16x16x32_bf16 v[56:59], v[76:79], v[104:107], v[56:59]
	v_mfma_f32_16x16x32_bf16 v[60:63], v[76:79], v[108:111], v[60:63]
	ds_read_b128 v[92:95], v139 offset:6144
	s_waitcnt lgkmcnt(3)
	v_mfma_f32_16x16x32_bf16 v[0:3], v[80:83], v[112:115], v[0:3]
	v_mfma_f32_16x16x32_bf16 v[4:7], v[80:83], v[116:119], v[4:7]
	v_mfma_f32_16x16x32_bf16 v[8:11], v[80:83], v[120:123], v[8:11]
	v_mfma_f32_16x16x32_bf16 v[12:15], v[80:83], v[124:127], v[12:15]
	s_waitcnt lgkmcnt(2)
	v_mfma_f32_16x16x32_bf16 v[16:19], v[84:87], v[112:115], v[16:19]
	v_mfma_f32_16x16x32_bf16 v[20:23], v[84:87], v[116:119], v[20:23]
	v_mfma_f32_16x16x32_bf16 v[24:27], v[84:87], v[120:123], v[24:27]
	v_mfma_f32_16x16x32_bf16 v[28:31], v[84:87], v[124:127], v[28:31]
	s_waitcnt lgkmcnt(1)
	v_mfma_f32_16x16x32_bf16 v[32:35], v[88:91], v[112:115], v[32:35]
	v_mfma_f32_16x16x32_bf16 v[36:39], v[88:91], v[116:119], v[36:39]
	v_mfma_f32_16x16x32_bf16 v[40:43], v[88:91], v[120:123], v[40:43]
	v_mfma_f32_16x16x32_bf16 v[44:47], v[88:91], v[124:127], v[44:47]
	s_waitcnt lgkmcnt(0)
	v_mfma_f32_16x16x32_bf16 v[48:51], v[92:95], v[112:115], v[48:51]
	v_mfma_f32_16x16x32_bf16 v[52:55], v[92:95], v[116:119], v[52:55]
	v_mfma_f32_16x16x32_bf16 v[56:59], v[92:95], v[120:123], v[56:59]
	v_mfma_f32_16x16x32_bf16 v[60:63], v[92:95], v[124:127], v[60:63]
	s_waitcnt vmcnt(0)
	s_barrier
	s_add_i32 s99, s99, 1
	s_cmp_eq_u32 s99, 16
	s_movk_i32 s0, 0x80
	s_cselect_b32 s0, 0xfffff880, s0
	s_cselect_b32 s99, 0, s99
	s_ashr_i32 s1, s0, 31
	s_add_u32 s26, s26, s0
	s_addc_u32 s27, s27, s1
	s_add_u32 s28, s28, s0
	s_addc_u32 s29, s29, s1
	s_mov_b32 m0, s7
	s_nop 0
	global_load_lds_dwordx4 v132, s[26:27] offset:0
	global_load_lds_dwordx4 v133, s[26:27] offset:1024
	global_load_lds_dwordx4 v134, s[26:27] offset:2048
	global_load_lds_dwordx4 v135, s[26:27] offset:3072
	s_mov_b32 m0, s8
	s_nop 0
	global_load_lds_dwordx4 v132, s[28:29] offset:0
	global_load_lds_dwordx4 v133, s[28:29] offset:1024
	global_load_lds_dwordx4 v134, s[28:29] offset:2048
	global_load_lds_dwordx4 v135, s[28:29] offset:3072
	ds_read_b128 v[64:67], v136 offset:0
	ds_read_b128 v[96:99], v140 offset:0
	ds_read_b128 v[100:103], v140 offset:2048
	ds_read_b128 v[104:107], v140 offset:4096
	ds_read_b128 v[108:111], v140 offset:6144
	ds_read_b128 v[68:71], v136 offset:2048
	ds_read_b128 v[72:75], v136 offset:4096
	ds_read_b128 v[76:79], v136 offset:6144
	s_waitcnt lgkmcnt(3)
	v_mfma_f32_16x16x32_bf16 v[0:3], v[64:67], v[96:99], v[0:3]
	v_mfma_f32_16x16x32_bf16 v[4:7], v[64:67], v[100:103], v[4:7]
	ds_read_b128 v[80:83], v137 offset:0
	v_mfma_f32_16x16x32_bf16 v[8:11], v[64:67], v[104:107], v[8:11]
	v_mfma_f32_16x16x32_bf16 v[12:15], v[64:67], v[108:111], v[12:15]
	ds_read_b128 v[112:115], v141 offset:0
	s_waitcnt lgkmcnt(4)
	v_mfma_f32_16x16x32_bf16 v[16:19], v[68:71], v[96:99], v[16:19]
	v_mfma_f32_16x16x32_bf16 v[20:23], v[68:71], v[100:103], v[20:23]
	ds_read_b128 v[116:119], v141 offset:2048
	v_mfma_f32_16x16x32_bf16 v[24:27], v[68:71], v[104:107], v[24:27]
	v_mfma_f32_16x16x32_bf16 v[28:31], v[68:71], v[108:111], v[28:31]
	ds_read_b128 v[120:123], v141 offset:4096
	s_waitcnt lgkmcnt(5)
	v_mfma_f32_16x16x32_bf16 v[32:35], v[72:75], v[96:99], v[32:35]
	v_mfma_f32_16x16x32_bf16 v[36:39], v[72:75], v[100:103], v[36:39]
	ds_read_b128 v[124:127], v141 offset:6144
	v_mfma_f32_16x16x32_bf16 v[40:43], v[72:75], v[104:107], v[40:43]
	v_mfma_f32_16x16x32_bf16 v[44:47], v[72:75], v[108:111], v[44:47]
	ds_read_b128 v[84:87], v137 offset:2048
	s_waitcnt lgkmcnt(6)
	v_mfma_f32_16x16x32_bf16 v[48:51], v[76:79], v[96:99], v[48:51]
	v_mfma_f32_16x16x32_bf16 v[52:55], v[76:79], v[100:103], v[52:55]
	ds_read_b128 v[88:91], v137 offset:4096
	v_mfma_f32_16x16x32_bf16 v[56:59], v[76:79], v[104:107], v[56:59]
	v_mfma_f32_16x16x32_bf16 v[60:63], v[76:79], v[108:111], v[60:63]
	ds_read_b128 v[92:95], v137 offset:6144
	s_waitcnt lgkmcnt(3)
	v_mfma_f32_16x16x32_bf16 v[0:3], v[80:83], v[112:115], v[0:3]
	v_mfma_f32_16x16x32_bf16 v[4:7], v[80:83], v[116:119], v[4:7]
	v_mfma_f32_16x16x32_bf16 v[8:11], v[80:83], v[120:123], v[8:11]
	v_mfma_f32_16x16x32_bf16 v[12:15], v[80:83], v[124:127], v[12:15]
	s_waitcnt lgkmcnt(2)
	v_mfma_f32_16x16x32_bf16 v[16:19], v[84:87], v[112:115], v[16:19]
	v_mfma_f32_16x16x32_bf16 v[20:23], v[84:87], v[116:119], v[20:23]
	v_mfma_f32_16x16x32_bf16 v[24:27], v[84:87], v[120:123], v[24:27]
	v_mfma_f32_16x16x32_bf16 v[28:31], v[84:87], v[124:127], v[28:31]
	s_waitcnt lgkmcnt(1)
	v_mfma_f32_16x16x32_bf16 v[32:35], v[88:91], v[112:115], v[32:35]
	v_mfma_f32_16x16x32_bf16 v[36:39], v[88:91], v[116:119], v[36:39]
	v_mfma_f32_16x16x32_bf16 v[40:43], v[88:91], v[120:123], v[40:43]
	v_mfma_f32_16x16x32_bf16 v[44:47], v[88:91], v[124:127], v[44:47]
	s_waitcnt lgkmcnt(0)
	v_mfma_f32_16x16x32_bf16 v[48:51], v[92:95], v[112:115], v[48:51]
	v_mfma_f32_16x16x32_bf16 v[52:55], v[92:95], v[116:119], v[52:55]
	v_mfma_f32_16x16x32_bf16 v[56:59], v[92:95], v[120:123], v[56:59]
	v_mfma_f32_16x16x32_bf16 v[60:63], v[92:95], v[124:127], v[60:63]
	s_waitcnt vmcnt(0)
	s_barrier
	s_add_i32 s99, s99, 1
	s_cmp_eq_u32 s99, 16
	s_movk_i32 s0, 0x80
	s_cselect_b32 s0, 0xfffff880, s0
	s_cselect_b32 s99, 0, s99
	s_ashr_i32 s1, s0, 31
	s_add_u32 s26, s26, s0
	s_addc_u32 s27, s27, s1
	s_add_u32 s28, s28, s0
	s_addc_u32 s29, s29, s1
	s_mov_b32 m0, s5
	s_nop 0
	global_load_lds_dwordx4 v132, s[26:27] offset:0
	global_load_lds_dwordx4 v133, s[26:27] offset:1024
	global_load_lds_dwordx4 v134, s[26:27] offset:2048
	global_load_lds_dwordx4 v135, s[26:27] offset:3072
	s_mov_b32 m0, s6
	s_nop 0
	global_load_lds_dwordx4 v132, s[28:29] offset:0
	global_load_lds_dwordx4 v133, s[28:29] offset:1024
	global_load_lds_dwordx4 v134, s[28:29] offset:2048
	global_load_lds_dwordx4 v135, s[28:29] offset:3072
	ds_read_b128 v[64:67], v138 offset:0
	ds_read_b128 v[96:99], v142 offset:0
	ds_read_b128 v[100:103], v142 offset:2048
	ds_read_b128 v[104:107], v142 offset:4096
	ds_read_b128 v[108:111], v142 offset:6144
	ds_read_b128 v[68:71], v138 offset:2048
	ds_read_b128 v[72:75], v138 offset:4096
	ds_read_b128 v[76:79], v138 offset:6144
	s_waitcnt lgkmcnt(3)
	v_mfma_f32_16x16x32_bf16 v[0:3], v[64:67], v[96:99], v[0:3]
	v_mfma_f32_16x16x32_bf16 v[4:7], v[64:67], v[100:103], v[4:7]
	ds_read_b128 v[80:83], v139 offset:0
	v_mfma_f32_16x16x32_bf16 v[8:11], v[64:67], v[104:107], v[8:11]
	v_mfma_f32_16x16x32_bf16 v[12:15], v[64:67], v[108:111], v[12:15]
	ds_read_b128 v[112:115], v143 offset:0
	s_waitcnt lgkmcnt(4)
	v_mfma_f32_16x16x32_bf16 v[16:19], v[68:71], v[96:99], v[16:19]
	v_mfma_f32_16x16x32_bf16 v[20:23], v[68:71], v[100:103], v[20:23]
	ds_read_b128 v[116:119], v143 offset:2048
	v_mfma_f32_16x16x32_bf16 v[24:27], v[68:71], v[104:107], v[24:27]
	v_mfma_f32_16x16x32_bf16 v[28:31], v[68:71], v[108:111], v[28:31]
	ds_read_b128 v[120:123], v143 offset:4096
	s_waitcnt lgkmcnt(5)
	v_mfma_f32_16x16x32_bf16 v[32:35], v[72:75], v[96:99], v[32:35]
	v_mfma_f32_16x16x32_bf16 v[36:39], v[72:75], v[100:103], v[36:39]
	ds_read_b128 v[124:127], v143 offset:6144
	v_mfma_f32_16x16x32_bf16 v[40:43], v[72:75], v[104:107], v[40:43]
	v_mfma_f32_16x16x32_bf16 v[44:47], v[72:75], v[108:111], v[44:47]
	ds_read_b128 v[84:87], v139 offset:2048
	s_waitcnt lgkmcnt(6)
	v_mfma_f32_16x16x32_bf16 v[48:51], v[76:79], v[96:99], v[48:51]
	v_mfma_f32_16x16x32_bf16 v[52:55], v[76:79], v[100:103], v[52:55]
	ds_read_b128 v[88:91], v139 offset:4096
	v_mfma_f32_16x16x32_bf16 v[56:59], v[76:79], v[104:107], v[56:59]
	v_mfma_f32_16x16x32_bf16 v[60:63], v[76:79], v[108:111], v[60:63]
	ds_read_b128 v[92:95], v139 offset:6144
	s_waitcnt lgkmcnt(3)
	v_mfma_f32_16x16x32_bf16 v[0:3], v[80:83], v[112:115], v[0:3]
	v_mfma_f32_16x16x32_bf16 v[4:7], v[80:83], v[116:119], v[4:7]
	v_mfma_f32_16x16x32_bf16 v[8:11], v[80:83], v[120:123], v[8:11]
	v_mfma_f32_16x16x32_bf16 v[12:15], v[80:83], v[124:127], v[12:15]
	s_waitcnt lgkmcnt(2)
	v_mfma_f32_16x16x32_bf16 v[16:19], v[84:87], v[112:115], v[16:19]
	v_mfma_f32_16x16x32_bf16 v[20:23], v[84:87], v[116:119], v[20:23]
	v_mfma_f32_16x16x32_bf16 v[24:27], v[84:87], v[120:123], v[24:27]
	v_mfma_f32_16x16x32_bf16 v[28:31], v[84:87], v[124:127], v[28:31]
	s_waitcnt lgkmcnt(1)
	v_mfma_f32_16x16x32_bf16 v[32:35], v[88:91], v[112:115], v[32:35]
	v_mfma_f32_16x16x32_bf16 v[36:39], v[88:91], v[116:119], v[36:39]
	v_mfma_f32_16x16x32_bf16 v[40:43], v[88:91], v[120:123], v[40:43]
	v_mfma_f32_16x16x32_bf16 v[44:47], v[88:91], v[124:127], v[44:47]
	s_waitcnt lgkmcnt(0)
	v_mfma_f32_16x16x32_bf16 v[48:51], v[92:95], v[112:115], v[48:51]
	v_mfma_f32_16x16x32_bf16 v[52:55], v[92:95], v[116:119], v[52:55]
	v_mfma_f32_16x16x32_bf16 v[56:59], v[92:95], v[120:123], v[56:59]
	v_mfma_f32_16x16x32_bf16 v[60:63], v[92:95], v[124:127], v[60:63]
	s_waitcnt vmcnt(0)
	s_barrier
	s_add_i32 s99, s99, 1
	s_cmp_eq_u32 s99, 16
	s_movk_i32 s0, 0x80
	s_cselect_b32 s0, 0xfffff880, s0
	s_cselect_b32 s99, 0, s99
	s_ashr_i32 s1, s0, 31
	s_add_u32 s26, s26, s0
	s_addc_u32 s27, s27, s1
	s_add_u32 s28, s28, s0
	s_addc_u32 s29, s29, s1
	s_mov_b32 m0, s7
	s_nop 0
	global_load_lds_dwordx4 v132, s[26:27] offset:0
	global_load_lds_dwordx4 v133, s[26:27] offset:1024
	global_load_lds_dwordx4 v134, s[26:27] offset:2048
	global_load_lds_dwordx4 v135, s[26:27] offset:3072
	s_mov_b32 m0, s8
	s_nop 0
	global_load_lds_dwordx4 v132, s[28:29] offset:0
	global_load_lds_dwordx4 v133, s[28:29] offset:1024
	global_load_lds_dwordx4 v134, s[28:29] offset:2048
	global_load_lds_dwordx4 v135, s[28:29] offset:3072
	ds_read_b128 v[64:67], v136 offset:0
	ds_read_b128 v[96:99], v140 offset:0
	ds_read_b128 v[100:103], v140 offset:2048
	ds_read_b128 v[104:107], v140 offset:4096
	ds_read_b128 v[108:111], v140 offset:6144
	ds_read_b128 v[68:71], v136 offset:2048
	ds_read_b128 v[72:75], v136 offset:4096
	ds_read_b128 v[76:79], v136 offset:6144
	s_waitcnt lgkmcnt(3)
	v_mfma_f32_16x16x32_bf16 v[0:3], v[64:67], v[96:99], v[0:3]
	v_mfma_f32_16x16x32_bf16 v[4:7], v[64:67], v[100:103], v[4:7]
	ds_read_b128 v[80:83], v137 offset:0
	v_mfma_f32_16x16x32_bf16 v[8:11], v[64:67], v[104:107], v[8:11]
	v_mfma_f32_16x16x32_bf16 v[12:15], v[64:67], v[108:111], v[12:15]
	ds_read_b128 v[112:115], v141 offset:0
	s_waitcnt lgkmcnt(4)
	v_mfma_f32_16x16x32_bf16 v[16:19], v[68:71], v[96:99], v[16:19]
	v_mfma_f32_16x16x32_bf16 v[20:23], v[68:71], v[100:103], v[20:23]
	ds_read_b128 v[116:119], v141 offset:2048
	v_mfma_f32_16x16x32_bf16 v[24:27], v[68:71], v[104:107], v[24:27]
	v_mfma_f32_16x16x32_bf16 v[28:31], v[68:71], v[108:111], v[28:31]
	ds_read_b128 v[120:123], v141 offset:4096
	s_waitcnt lgkmcnt(5)
	v_mfma_f32_16x16x32_bf16 v[32:35], v[72:75], v[96:99], v[32:35]
	v_mfma_f32_16x16x32_bf16 v[36:39], v[72:75], v[100:103], v[36:39]
	ds_read_b128 v[124:127], v141 offset:6144
	v_mfma_f32_16x16x32_bf16 v[40:43], v[72:75], v[104:107], v[40:43]
	v_mfma_f32_16x16x32_bf16 v[44:47], v[72:75], v[108:111], v[44:47]
	ds_read_b128 v[84:87], v137 offset:2048
	s_waitcnt lgkmcnt(6)
	v_mfma_f32_16x16x32_bf16 v[48:51], v[76:79], v[96:99], v[48:51]
	v_mfma_f32_16x16x32_bf16 v[52:55], v[76:79], v[100:103], v[52:55]
	ds_read_b128 v[88:91], v137 offset:4096
	v_mfma_f32_16x16x32_bf16 v[56:59], v[76:79], v[104:107], v[56:59]
	v_mfma_f32_16x16x32_bf16 v[60:63], v[76:79], v[108:111], v[60:63]
	ds_read_b128 v[92:95], v137 offset:6144
	s_waitcnt lgkmcnt(3)
	v_mfma_f32_16x16x32_bf16 v[0:3], v[80:83], v[112:115], v[0:3]
	v_mfma_f32_16x16x32_bf16 v[4:7], v[80:83], v[116:119], v[4:7]
	v_mfma_f32_16x16x32_bf16 v[8:11], v[80:83], v[120:123], v[8:11]
	v_mfma_f32_16x16x32_bf16 v[12:15], v[80:83], v[124:127], v[12:15]
	s_waitcnt lgkmcnt(2)
	v_mfma_f32_16x16x32_bf16 v[16:19], v[84:87], v[112:115], v[16:19]
	v_mfma_f32_16x16x32_bf16 v[20:23], v[84:87], v[116:119], v[20:23]
	v_mfma_f32_16x16x32_bf16 v[24:27], v[84:87], v[120:123], v[24:27]
	v_mfma_f32_16x16x32_bf16 v[28:31], v[84:87], v[124:127], v[28:31]
	s_waitcnt lgkmcnt(1)
	v_mfma_f32_16x16x32_bf16 v[32:35], v[88:91], v[112:115], v[32:35]
	v_mfma_f32_16x16x32_bf16 v[36:39], v[88:91], v[116:119], v[36:39]
	v_mfma_f32_16x16x32_bf16 v[40:43], v[88:91], v[120:123], v[40:43]
	v_mfma_f32_16x16x32_bf16 v[44:47], v[88:91], v[124:127], v[44:47]
	s_waitcnt lgkmcnt(0)
	v_mfma_f32_16x16x32_bf16 v[48:51], v[92:95], v[112:115], v[48:51]
	v_mfma_f32_16x16x32_bf16 v[52:55], v[92:95], v[116:119], v[52:55]
	v_mfma_f32_16x16x32_bf16 v[56:59], v[92:95], v[120:123], v[56:59]
	v_mfma_f32_16x16x32_bf16 v[60:63], v[92:95], v[124:127], v[60:63]
	s_waitcnt vmcnt(0)
	s_barrier
	s_add_i32 s99, s99, 1
	s_cmp_eq_u32 s99, 16
	s_movk_i32 s0, 0x80
	s_cselect_b32 s0, 0xfffff880, s0
	s_cselect_b32 s99, 0, s99
	s_ashr_i32 s1, s0, 31
	s_add_u32 s26, s26, s0
	s_addc_u32 s27, s27, s1
	s_add_u32 s28, s28, s0
	s_addc_u32 s29, s29, s1
	s_mov_b32 m0, s5
	s_nop 0
	global_load_lds_dwordx4 v132, s[26:27] offset:0
	global_load_lds_dwordx4 v133, s[26:27] offset:1024
	global_load_lds_dwordx4 v134, s[26:27] offset:2048
	global_load_lds_dwordx4 v135, s[26:27] offset:3072
	s_mov_b32 m0, s6
	s_nop 0
	global_load_lds_dwordx4 v132, s[28:29] offset:0
	global_load_lds_dwordx4 v133, s[28:29] offset:1024
	global_load_lds_dwordx4 v134, s[28:29] offset:2048
	global_load_lds_dwordx4 v135, s[28:29] offset:3072
	ds_read_b128 v[64:67], v138 offset:0
	ds_read_b128 v[96:99], v142 offset:0
	ds_read_b128 v[100:103], v142 offset:2048
	ds_read_b128 v[104:107], v142 offset:4096
	ds_read_b128 v[108:111], v142 offset:6144
	ds_read_b128 v[68:71], v138 offset:2048
	ds_read_b128 v[72:75], v138 offset:4096
	ds_read_b128 v[76:79], v138 offset:6144
	s_waitcnt lgkmcnt(3)
	v_mfma_f32_16x16x32_bf16 v[0:3], v[64:67], v[96:99], v[0:3]
	v_mfma_f32_16x16x32_bf16 v[4:7], v[64:67], v[100:103], v[4:7]
	ds_read_b128 v[80:83], v139 offset:0
	v_mfma_f32_16x16x32_bf16 v[8:11], v[64:67], v[104:107], v[8:11]
	v_mfma_f32_16x16x32_bf16 v[12:15], v[64:67], v[108:111], v[12:15]
	ds_read_b128 v[112:115], v143 offset:0
	s_waitcnt lgkmcnt(4)
	v_mfma_f32_16x16x32_bf16 v[16:19], v[68:71], v[96:99], v[16:19]
	v_mfma_f32_16x16x32_bf16 v[20:23], v[68:71], v[100:103], v[20:23]
	ds_read_b128 v[116:119], v143 offset:2048
	v_mfma_f32_16x16x32_bf16 v[24:27], v[68:71], v[104:107], v[24:27]
	v_mfma_f32_16x16x32_bf16 v[28:31], v[68:71], v[108:111], v[28:31]
	ds_read_b128 v[120:123], v143 offset:4096
	s_waitcnt lgkmcnt(5)
	v_mfma_f32_16x16x32_bf16 v[32:35], v[72:75], v[96:99], v[32:35]
	v_mfma_f32_16x16x32_bf16 v[36:39], v[72:75], v[100:103], v[36:39]
	ds_read_b128 v[124:127], v143 offset:6144
	v_mfma_f32_16x16x32_bf16 v[40:43], v[72:75], v[104:107], v[40:43]
	v_mfma_f32_16x16x32_bf16 v[44:47], v[72:75], v[108:111], v[44:47]
	ds_read_b128 v[84:87], v139 offset:2048
	s_waitcnt lgkmcnt(6)
	v_mfma_f32_16x16x32_bf16 v[48:51], v[76:79], v[96:99], v[48:51]
	v_mfma_f32_16x16x32_bf16 v[52:55], v[76:79], v[100:103], v[52:55]
	ds_read_b128 v[88:91], v139 offset:4096
	v_mfma_f32_16x16x32_bf16 v[56:59], v[76:79], v[104:107], v[56:59]
	v_mfma_f32_16x16x32_bf16 v[60:63], v[76:79], v[108:111], v[60:63]
	ds_read_b128 v[92:95], v139 offset:6144
	s_waitcnt lgkmcnt(3)
	v_mfma_f32_16x16x32_bf16 v[0:3], v[80:83], v[112:115], v[0:3]
	v_mfma_f32_16x16x32_bf16 v[4:7], v[80:83], v[116:119], v[4:7]
	v_mfma_f32_16x16x32_bf16 v[8:11], v[80:83], v[120:123], v[8:11]
	v_mfma_f32_16x16x32_bf16 v[12:15], v[80:83], v[124:127], v[12:15]
	s_waitcnt lgkmcnt(2)
	v_mfma_f32_16x16x32_bf16 v[16:19], v[84:87], v[112:115], v[16:19]
	v_mfma_f32_16x16x32_bf16 v[20:23], v[84:87], v[116:119], v[20:23]
	v_mfma_f32_16x16x32_bf16 v[24:27], v[84:87], v[120:123], v[24:27]
	v_mfma_f32_16x16x32_bf16 v[28:31], v[84:87], v[124:127], v[28:31]
	s_waitcnt lgkmcnt(1)
	v_mfma_f32_16x16x32_bf16 v[32:35], v[88:91], v[112:115], v[32:35]
	v_mfma_f32_16x16x32_bf16 v[36:39], v[88:91], v[116:119], v[36:39]
	v_mfma_f32_16x16x32_bf16 v[40:43], v[88:91], v[120:123], v[40:43]
	v_mfma_f32_16x16x32_bf16 v[44:47], v[88:91], v[124:127], v[44:47]
	s_waitcnt lgkmcnt(0)
	v_mfma_f32_16x16x32_bf16 v[48:51], v[92:95], v[112:115], v[48:51]
	v_mfma_f32_16x16x32_bf16 v[52:55], v[92:95], v[116:119], v[52:55]
	v_mfma_f32_16x16x32_bf16 v[56:59], v[92:95], v[120:123], v[56:59]
	v_mfma_f32_16x16x32_bf16 v[60:63], v[92:95], v[124:127], v[60:63]
	s_waitcnt vmcnt(0)
	s_barrier
	s_add_i32 s99, s99, 1
	s_cmp_eq_u32 s99, 16
	s_movk_i32 s0, 0x80
	s_cselect_b32 s0, 0xfffff880, s0
	s_cselect_b32 s99, 0, s99
	s_ashr_i32 s1, s0, 31
	s_add_u32 s26, s26, s0
	s_addc_u32 s27, s27, s1
	s_add_u32 s28, s28, s0
	s_addc_u32 s29, s29, s1
	s_mov_b32 m0, s7
	s_nop 0
	global_load_lds_dwordx4 v132, s[26:27] offset:0
	global_load_lds_dwordx4 v133, s[26:27] offset:1024
	global_load_lds_dwordx4 v134, s[26:27] offset:2048
	global_load_lds_dwordx4 v135, s[26:27] offset:3072
	s_mov_b32 m0, s8
	s_nop 0
	global_load_lds_dwordx4 v132, s[28:29] offset:0
	global_load_lds_dwordx4 v133, s[28:29] offset:1024
	global_load_lds_dwordx4 v134, s[28:29] offset:2048
	global_load_lds_dwordx4 v135, s[28:29] offset:3072
	ds_read_b128 v[64:67], v136 offset:0
	ds_read_b128 v[96:99], v140 offset:0
	ds_read_b128 v[100:103], v140 offset:2048
	ds_read_b128 v[104:107], v140 offset:4096
	ds_read_b128 v[108:111], v140 offset:6144
	ds_read_b128 v[68:71], v136 offset:2048
	ds_read_b128 v[72:75], v136 offset:4096
	ds_read_b128 v[76:79], v136 offset:6144
	s_waitcnt lgkmcnt(3)
	v_mfma_f32_16x16x32_bf16 v[0:3], v[64:67], v[96:99], v[0:3]
	v_mfma_f32_16x16x32_bf16 v[4:7], v[64:67], v[100:103], v[4:7]
	ds_read_b128 v[80:83], v137 offset:0
	v_mfma_f32_16x16x32_bf16 v[8:11], v[64:67], v[104:107], v[8:11]
	v_mfma_f32_16x16x32_bf16 v[12:15], v[64:67], v[108:111], v[12:15]
	ds_read_b128 v[112:115], v141 offset:0
	s_waitcnt lgkmcnt(4)
	v_mfma_f32_16x16x32_bf16 v[16:19], v[68:71], v[96:99], v[16:19]
	v_mfma_f32_16x16x32_bf16 v[20:23], v[68:71], v[100:103], v[20:23]
	ds_read_b128 v[116:119], v141 offset:2048
	v_mfma_f32_16x16x32_bf16 v[24:27], v[68:71], v[104:107], v[24:27]
	v_mfma_f32_16x16x32_bf16 v[28:31], v[68:71], v[108:111], v[28:31]
	ds_read_b128 v[120:123], v141 offset:4096
	s_waitcnt lgkmcnt(5)
	v_mfma_f32_16x16x32_bf16 v[32:35], v[72:75], v[96:99], v[32:35]
	v_mfma_f32_16x16x32_bf16 v[36:39], v[72:75], v[100:103], v[36:39]
	ds_read_b128 v[124:127], v141 offset:6144
	v_mfma_f32_16x16x32_bf16 v[40:43], v[72:75], v[104:107], v[40:43]
	v_mfma_f32_16x16x32_bf16 v[44:47], v[72:75], v[108:111], v[44:47]
	ds_read_b128 v[84:87], v137 offset:2048
	s_waitcnt lgkmcnt(6)
	v_mfma_f32_16x16x32_bf16 v[48:51], v[76:79], v[96:99], v[48:51]
	v_mfma_f32_16x16x32_bf16 v[52:55], v[76:79], v[100:103], v[52:55]
	ds_read_b128 v[88:91], v137 offset:4096
	v_mfma_f32_16x16x32_bf16 v[56:59], v[76:79], v[104:107], v[56:59]
	v_mfma_f32_16x16x32_bf16 v[60:63], v[76:79], v[108:111], v[60:63]
	ds_read_b128 v[92:95], v137 offset:6144
	s_waitcnt lgkmcnt(3)
	v_mfma_f32_16x16x32_bf16 v[0:3], v[80:83], v[112:115], v[0:3]
	v_mfma_f32_16x16x32_bf16 v[4:7], v[80:83], v[116:119], v[4:7]
	v_mfma_f32_16x16x32_bf16 v[8:11], v[80:83], v[120:123], v[8:11]
	v_mfma_f32_16x16x32_bf16 v[12:15], v[80:83], v[124:127], v[12:15]
	s_waitcnt lgkmcnt(2)
	v_mfma_f32_16x16x32_bf16 v[16:19], v[84:87], v[112:115], v[16:19]
	v_mfma_f32_16x16x32_bf16 v[20:23], v[84:87], v[116:119], v[20:23]
	v_mfma_f32_16x16x32_bf16 v[24:27], v[84:87], v[120:123], v[24:27]
	v_mfma_f32_16x16x32_bf16 v[28:31], v[84:87], v[124:127], v[28:31]
	s_waitcnt lgkmcnt(1)
	v_mfma_f32_16x16x32_bf16 v[32:35], v[88:91], v[112:115], v[32:35]
	v_mfma_f32_16x16x32_bf16 v[36:39], v[88:91], v[116:119], v[36:39]
	v_mfma_f32_16x16x32_bf16 v[40:43], v[88:91], v[120:123], v[40:43]
	v_mfma_f32_16x16x32_bf16 v[44:47], v[88:91], v[124:127], v[44:47]
	s_waitcnt lgkmcnt(0)
	v_mfma_f32_16x16x32_bf16 v[48:51], v[92:95], v[112:115], v[48:51]
	v_mfma_f32_16x16x32_bf16 v[52:55], v[92:95], v[116:119], v[52:55]
	v_mfma_f32_16x16x32_bf16 v[56:59], v[92:95], v[120:123], v[56:59]
	v_mfma_f32_16x16x32_bf16 v[60:63], v[92:95], v[124:127], v[60:63]
	s_waitcnt vmcnt(0)
	s_barrier
	s_add_i32 s99, s99, 1
	s_cmp_eq_u32 s99, 16
	s_movk_i32 s0, 0x80
	s_cselect_b32 s0, 0xfffff880, s0
	s_cselect_b32 s99, 0, s99
	s_ashr_i32 s1, s0, 31
	s_add_u32 s26, s26, s0
	s_addc_u32 s27, s27, s1
	s_add_u32 s28, s28, s0
	s_addc_u32 s29, s29, s1
	s_mov_b32 m0, s5
	s_nop 0
	global_load_lds_dwordx4 v132, s[26:27] offset:0
	global_load_lds_dwordx4 v133, s[26:27] offset:1024
	global_load_lds_dwordx4 v134, s[26:27] offset:2048
	global_load_lds_dwordx4 v135, s[26:27] offset:3072
	s_mov_b32 m0, s6
	s_nop 0
	global_load_lds_dwordx4 v132, s[28:29] offset:0
	global_load_lds_dwordx4 v133, s[28:29] offset:1024
	global_load_lds_dwordx4 v134, s[28:29] offset:2048
	global_load_lds_dwordx4 v135, s[28:29] offset:3072
	ds_read_b128 v[64:67], v138 offset:0
	ds_read_b128 v[96:99], v142 offset:0
	ds_read_b128 v[100:103], v142 offset:2048
	ds_read_b128 v[104:107], v142 offset:4096
	ds_read_b128 v[108:111], v142 offset:6144
	ds_read_b128 v[68:71], v138 offset:2048
	ds_read_b128 v[72:75], v138 offset:4096
	ds_read_b128 v[76:79], v138 offset:6144
	s_waitcnt lgkmcnt(3)
	v_mfma_f32_16x16x32_bf16 v[0:3], v[64:67], v[96:99], v[0:3]
	v_mfma_f32_16x16x32_bf16 v[4:7], v[64:67], v[100:103], v[4:7]
	ds_read_b128 v[80:83], v139 offset:0
	v_mfma_f32_16x16x32_bf16 v[8:11], v[64:67], v[104:107], v[8:11]
	v_mfma_f32_16x16x32_bf16 v[12:15], v[64:67], v[108:111], v[12:15]
	ds_read_b128 v[112:115], v143 offset:0
	s_waitcnt lgkmcnt(4)
	v_mfma_f32_16x16x32_bf16 v[16:19], v[68:71], v[96:99], v[16:19]
	v_mfma_f32_16x16x32_bf16 v[20:23], v[68:71], v[100:103], v[20:23]
	ds_read_b128 v[116:119], v143 offset:2048
	v_mfma_f32_16x16x32_bf16 v[24:27], v[68:71], v[104:107], v[24:27]
	v_mfma_f32_16x16x32_bf16 v[28:31], v[68:71], v[108:111], v[28:31]
	ds_read_b128 v[120:123], v143 offset:4096
	s_waitcnt lgkmcnt(5)
	v_mfma_f32_16x16x32_bf16 v[32:35], v[72:75], v[96:99], v[32:35]
	v_mfma_f32_16x16x32_bf16 v[36:39], v[72:75], v[100:103], v[36:39]
	ds_read_b128 v[124:127], v143 offset:6144
	v_mfma_f32_16x16x32_bf16 v[40:43], v[72:75], v[104:107], v[40:43]
	v_mfma_f32_16x16x32_bf16 v[44:47], v[72:75], v[108:111], v[44:47]
	ds_read_b128 v[84:87], v139 offset:2048
	s_waitcnt lgkmcnt(6)
	v_mfma_f32_16x16x32_bf16 v[48:51], v[76:79], v[96:99], v[48:51]
	v_mfma_f32_16x16x32_bf16 v[52:55], v[76:79], v[100:103], v[52:55]
	ds_read_b128 v[88:91], v139 offset:4096
	v_mfma_f32_16x16x32_bf16 v[56:59], v[76:79], v[104:107], v[56:59]
	v_mfma_f32_16x16x32_bf16 v[60:63], v[76:79], v[108:111], v[60:63]
	ds_read_b128 v[92:95], v139 offset:6144
	s_waitcnt lgkmcnt(3)
	v_mfma_f32_16x16x32_bf16 v[0:3], v[80:83], v[112:115], v[0:3]
	v_mfma_f32_16x16x32_bf16 v[4:7], v[80:83], v[116:119], v[4:7]
	v_mfma_f32_16x16x32_bf16 v[8:11], v[80:83], v[120:123], v[8:11]
	v_mfma_f32_16x16x32_bf16 v[12:15], v[80:83], v[124:127], v[12:15]
	s_waitcnt lgkmcnt(2)
	v_mfma_f32_16x16x32_bf16 v[16:19], v[84:87], v[112:115], v[16:19]
	v_mfma_f32_16x16x32_bf16 v[20:23], v[84:87], v[116:119], v[20:23]
	v_mfma_f32_16x16x32_bf16 v[24:27], v[84:87], v[120:123], v[24:27]
	v_mfma_f32_16x16x32_bf16 v[28:31], v[84:87], v[124:127], v[28:31]
	s_waitcnt lgkmcnt(1)
	v_mfma_f32_16x16x32_bf16 v[32:35], v[88:91], v[112:115], v[32:35]
	v_mfma_f32_16x16x32_bf16 v[36:39], v[88:91], v[116:119], v[36:39]
	v_mfma_f32_16x16x32_bf16 v[40:43], v[88:91], v[120:123], v[40:43]
	v_mfma_f32_16x16x32_bf16 v[44:47], v[88:91], v[124:127], v[44:47]
	s_waitcnt lgkmcnt(0)
	v_mfma_f32_16x16x32_bf16 v[48:51], v[92:95], v[112:115], v[48:51]
	v_mfma_f32_16x16x32_bf16 v[52:55], v[92:95], v[116:119], v[52:55]
	v_mfma_f32_16x16x32_bf16 v[56:59], v[92:95], v[120:123], v[56:59]
	v_mfma_f32_16x16x32_bf16 v[60:63], v[92:95], v[124:127], v[60:63]
	s_waitcnt vmcnt(0)
	s_barrier
	s_add_i32 s99, s99, 1
	s_cmp_eq_u32 s99, 16
	s_movk_i32 s0, 0x80
	s_cselect_b32 s0, 0xfffff880, s0
	s_cselect_b32 s99, 0, s99
	s_ashr_i32 s1, s0, 31
	s_add_u32 s26, s26, s0
	s_addc_u32 s27, s27, s1
	s_add_u32 s28, s28, s0
	s_addc_u32 s29, s29, s1
	s_mov_b32 m0, s7
	s_nop 0
	global_load_lds_dwordx4 v132, s[26:27] offset:0
	global_load_lds_dwordx4 v133, s[26:27] offset:1024
	global_load_lds_dwordx4 v134, s[26:27] offset:2048
	global_load_lds_dwordx4 v135, s[26:27] offset:3072
	s_mov_b32 m0, s8
	s_nop 0
	global_load_lds_dwordx4 v132, s[28:29] offset:0
	global_load_lds_dwordx4 v133, s[28:29] offset:1024
	global_load_lds_dwordx4 v134, s[28:29] offset:2048
	global_load_lds_dwordx4 v135, s[28:29] offset:3072
	ds_read_b128 v[64:67], v136 offset:0
	ds_read_b128 v[96:99], v140 offset:0
	ds_read_b128 v[100:103], v140 offset:2048
	ds_read_b128 v[104:107], v140 offset:4096
	ds_read_b128 v[108:111], v140 offset:6144
	ds_read_b128 v[68:71], v136 offset:2048
	ds_read_b128 v[72:75], v136 offset:4096
	ds_read_b128 v[76:79], v136 offset:6144
	s_waitcnt lgkmcnt(3)
	v_mfma_f32_16x16x32_bf16 v[0:3], v[64:67], v[96:99], v[0:3]
	v_mfma_f32_16x16x32_bf16 v[4:7], v[64:67], v[100:103], v[4:7]
	ds_read_b128 v[80:83], v137 offset:0
	v_mfma_f32_16x16x32_bf16 v[8:11], v[64:67], v[104:107], v[8:11]
	v_mfma_f32_16x16x32_bf16 v[12:15], v[64:67], v[108:111], v[12:15]
	ds_read_b128 v[112:115], v141 offset:0
	s_waitcnt lgkmcnt(4)
	v_mfma_f32_16x16x32_bf16 v[16:19], v[68:71], v[96:99], v[16:19]
	v_mfma_f32_16x16x32_bf16 v[20:23], v[68:71], v[100:103], v[20:23]
	ds_read_b128 v[116:119], v141 offset:2048
	v_mfma_f32_16x16x32_bf16 v[24:27], v[68:71], v[104:107], v[24:27]
	v_mfma_f32_16x16x32_bf16 v[28:31], v[68:71], v[108:111], v[28:31]
	ds_read_b128 v[120:123], v141 offset:4096
	s_waitcnt lgkmcnt(5)
	v_mfma_f32_16x16x32_bf16 v[32:35], v[72:75], v[96:99], v[32:35]
	v_mfma_f32_16x16x32_bf16 v[36:39], v[72:75], v[100:103], v[36:39]
	ds_read_b128 v[124:127], v141 offset:6144
	v_mfma_f32_16x16x32_bf16 v[40:43], v[72:75], v[104:107], v[40:43]
	v_mfma_f32_16x16x32_bf16 v[44:47], v[72:75], v[108:111], v[44:47]
	ds_read_b128 v[84:87], v137 offset:2048
	s_waitcnt lgkmcnt(6)
	v_mfma_f32_16x16x32_bf16 v[48:51], v[76:79], v[96:99], v[48:51]
	v_mfma_f32_16x16x32_bf16 v[52:55], v[76:79], v[100:103], v[52:55]
	ds_read_b128 v[88:91], v137 offset:4096
	v_mfma_f32_16x16x32_bf16 v[56:59], v[76:79], v[104:107], v[56:59]
	v_mfma_f32_16x16x32_bf16 v[60:63], v[76:79], v[108:111], v[60:63]
	ds_read_b128 v[92:95], v137 offset:6144
	s_waitcnt lgkmcnt(3)
	v_mfma_f32_16x16x32_bf16 v[0:3], v[80:83], v[112:115], v[0:3]
	v_mfma_f32_16x16x32_bf16 v[4:7], v[80:83], v[116:119], v[4:7]
	v_mfma_f32_16x16x32_bf16 v[8:11], v[80:83], v[120:123], v[8:11]
	v_mfma_f32_16x16x32_bf16 v[12:15], v[80:83], v[124:127], v[12:15]
	s_waitcnt lgkmcnt(2)
	v_mfma_f32_16x16x32_bf16 v[16:19], v[84:87], v[112:115], v[16:19]
	v_mfma_f32_16x16x32_bf16 v[20:23], v[84:87], v[116:119], v[20:23]
	v_mfma_f32_16x16x32_bf16 v[24:27], v[84:87], v[120:123], v[24:27]
	v_mfma_f32_16x16x32_bf16 v[28:31], v[84:87], v[124:127], v[28:31]
	s_waitcnt lgkmcnt(1)
	v_mfma_f32_16x16x32_bf16 v[32:35], v[88:91], v[112:115], v[32:35]
	v_mfma_f32_16x16x32_bf16 v[36:39], v[88:91], v[116:119], v[36:39]
	v_mfma_f32_16x16x32_bf16 v[40:43], v[88:91], v[120:123], v[40:43]
	v_mfma_f32_16x16x32_bf16 v[44:47], v[88:91], v[124:127], v[44:47]
	s_waitcnt lgkmcnt(0)
	v_mfma_f32_16x16x32_bf16 v[48:51], v[92:95], v[112:115], v[48:51]
	v_mfma_f32_16x16x32_bf16 v[52:55], v[92:95], v[116:119], v[52:55]
	v_mfma_f32_16x16x32_bf16 v[56:59], v[92:95], v[120:123], v[56:59]
	v_mfma_f32_16x16x32_bf16 v[60:63], v[92:95], v[124:127], v[60:63]
	s_waitcnt vmcnt(0)
	s_barrier
	s_add_i32 s99, s99, 1
	s_cmp_eq_u32 s99, 16
	s_movk_i32 s0, 0x80
	s_cselect_b32 s0, 0xfffff880, s0
	s_cselect_b32 s99, 0, s99
	s_ashr_i32 s1, s0, 31
	s_add_u32 s26, s26, s0
	s_addc_u32 s27, s27, s1
	s_add_u32 s28, s28, s0
	s_addc_u32 s29, s29, s1
	s_mov_b32 m0, s5
	s_nop 0
	global_load_lds_dwordx4 v132, s[26:27] offset:0
	global_load_lds_dwordx4 v133, s[26:27] offset:1024
	global_load_lds_dwordx4 v134, s[26:27] offset:2048
	global_load_lds_dwordx4 v135, s[26:27] offset:3072
	s_mov_b32 m0, s6
	s_nop 0
	global_load_lds_dwordx4 v132, s[28:29] offset:0
	global_load_lds_dwordx4 v133, s[28:29] offset:1024
	global_load_lds_dwordx4 v134, s[28:29] offset:2048
	global_load_lds_dwordx4 v135, s[28:29] offset:3072
	ds_read_b128 v[64:67], v138 offset:0
	ds_read_b128 v[96:99], v142 offset:0
	ds_read_b128 v[100:103], v142 offset:2048
	ds_read_b128 v[104:107], v142 offset:4096
	ds_read_b128 v[108:111], v142 offset:6144
	ds_read_b128 v[68:71], v138 offset:2048
	ds_read_b128 v[72:75], v138 offset:4096
	ds_read_b128 v[76:79], v138 offset:6144
	s_waitcnt lgkmcnt(3)
	v_mfma_f32_16x16x32_bf16 v[0:3], v[64:67], v[96:99], v[0:3]
	v_mfma_f32_16x16x32_bf16 v[4:7], v[64:67], v[100:103], v[4:7]
	ds_read_b128 v[80:83], v139 offset:0
	v_mfma_f32_16x16x32_bf16 v[8:11], v[64:67], v[104:107], v[8:11]
	v_mfma_f32_16x16x32_bf16 v[12:15], v[64:67], v[108:111], v[12:15]
	ds_read_b128 v[112:115], v143 offset:0
	s_waitcnt lgkmcnt(4)
	v_mfma_f32_16x16x32_bf16 v[16:19], v[68:71], v[96:99], v[16:19]
	v_mfma_f32_16x16x32_bf16 v[20:23], v[68:71], v[100:103], v[20:23]
	ds_read_b128 v[116:119], v143 offset:2048
	v_mfma_f32_16x16x32_bf16 v[24:27], v[68:71], v[104:107], v[24:27]
	v_mfma_f32_16x16x32_bf16 v[28:31], v[68:71], v[108:111], v[28:31]
	ds_read_b128 v[120:123], v143 offset:4096
	s_waitcnt lgkmcnt(5)
	v_mfma_f32_16x16x32_bf16 v[32:35], v[72:75], v[96:99], v[32:35]
	v_mfma_f32_16x16x32_bf16 v[36:39], v[72:75], v[100:103], v[36:39]
	ds_read_b128 v[124:127], v143 offset:6144
	v_mfma_f32_16x16x32_bf16 v[40:43], v[72:75], v[104:107], v[40:43]
	v_mfma_f32_16x16x32_bf16 v[44:47], v[72:75], v[108:111], v[44:47]
	ds_read_b128 v[84:87], v139 offset:2048
	s_waitcnt lgkmcnt(6)
	v_mfma_f32_16x16x32_bf16 v[48:51], v[76:79], v[96:99], v[48:51]
	v_mfma_f32_16x16x32_bf16 v[52:55], v[76:79], v[100:103], v[52:55]
	ds_read_b128 v[88:91], v139 offset:4096
	v_mfma_f32_16x16x32_bf16 v[56:59], v[76:79], v[104:107], v[56:59]
	v_mfma_f32_16x16x32_bf16 v[60:63], v[76:79], v[108:111], v[60:63]
	ds_read_b128 v[92:95], v139 offset:6144
	s_waitcnt lgkmcnt(3)
	v_mfma_f32_16x16x32_bf16 v[0:3], v[80:83], v[112:115], v[0:3]
	v_mfma_f32_16x16x32_bf16 v[4:7], v[80:83], v[116:119], v[4:7]
	v_mfma_f32_16x16x32_bf16 v[8:11], v[80:83], v[120:123], v[8:11]
	v_mfma_f32_16x16x32_bf16 v[12:15], v[80:83], v[124:127], v[12:15]
	s_waitcnt lgkmcnt(2)
	v_mfma_f32_16x16x32_bf16 v[16:19], v[84:87], v[112:115], v[16:19]
	v_mfma_f32_16x16x32_bf16 v[20:23], v[84:87], v[116:119], v[20:23]
	v_mfma_f32_16x16x32_bf16 v[24:27], v[84:87], v[120:123], v[24:27]
	v_mfma_f32_16x16x32_bf16 v[28:31], v[84:87], v[124:127], v[28:31]
	s_waitcnt lgkmcnt(1)
	v_mfma_f32_16x16x32_bf16 v[32:35], v[88:91], v[112:115], v[32:35]
	v_mfma_f32_16x16x32_bf16 v[36:39], v[88:91], v[116:119], v[36:39]
	v_mfma_f32_16x16x32_bf16 v[40:43], v[88:91], v[120:123], v[40:43]
	v_mfma_f32_16x16x32_bf16 v[44:47], v[88:91], v[124:127], v[44:47]
	s_waitcnt lgkmcnt(0)
	v_mfma_f32_16x16x32_bf16 v[48:51], v[92:95], v[112:115], v[48:51]
	v_mfma_f32_16x16x32_bf16 v[52:55], v[92:95], v[116:119], v[52:55]
	v_mfma_f32_16x16x32_bf16 v[56:59], v[92:95], v[120:123], v[56:59]
	v_mfma_f32_16x16x32_bf16 v[60:63], v[92:95], v[124:127], v[60:63]
	s_waitcnt vmcnt(0)
	s_barrier
	s_add_i32 s99, s99, 1
	s_cmp_eq_u32 s99, 16
	s_movk_i32 s0, 0x80
	s_cselect_b32 s0, 0xfffff880, s0
	s_cselect_b32 s99, 0, s99
	s_ashr_i32 s1, s0, 31
	s_add_u32 s26, s26, s0
	s_addc_u32 s27, s27, s1
	s_add_u32 s28, s28, s0
	s_addc_u32 s29, s29, s1
	s_mov_b32 m0, s7
	s_nop 0
	global_load_lds_dwordx4 v132, s[26:27] offset:0
	global_load_lds_dwordx4 v133, s[26:27] offset:1024
	global_load_lds_dwordx4 v134, s[26:27] offset:2048
	global_load_lds_dwordx4 v135, s[26:27] offset:3072
	s_mov_b32 m0, s8
	s_nop 0
	global_load_lds_dwordx4 v132, s[28:29] offset:0
	global_load_lds_dwordx4 v133, s[28:29] offset:1024
	global_load_lds_dwordx4 v134, s[28:29] offset:2048
	global_load_lds_dwordx4 v135, s[28:29] offset:3072
	ds_read_b128 v[64:67], v136 offset:0
	ds_read_b128 v[96:99], v140 offset:0
	ds_read_b128 v[100:103], v140 offset:2048
	ds_read_b128 v[104:107], v140 offset:4096
	ds_read_b128 v[108:111], v140 offset:6144
	ds_read_b128 v[68:71], v136 offset:2048
	ds_read_b128 v[72:75], v136 offset:4096
	ds_read_b128 v[76:79], v136 offset:6144
	s_waitcnt lgkmcnt(3)
	v_mfma_f32_16x16x32_bf16 v[0:3], v[64:67], v[96:99], v[0:3]
	v_mfma_f32_16x16x32_bf16 v[4:7], v[64:67], v[100:103], v[4:7]
	ds_read_b128 v[80:83], v137 offset:0
	v_mfma_f32_16x16x32_bf16 v[8:11], v[64:67], v[104:107], v[8:11]
	v_mfma_f32_16x16x32_bf16 v[12:15], v[64:67], v[108:111], v[12:15]
	ds_read_b128 v[112:115], v141 offset:0
	s_waitcnt lgkmcnt(4)
	v_mfma_f32_16x16x32_bf16 v[16:19], v[68:71], v[96:99], v[16:19]
	v_mfma_f32_16x16x32_bf16 v[20:23], v[68:71], v[100:103], v[20:23]
	ds_read_b128 v[116:119], v141 offset:2048
	v_mfma_f32_16x16x32_bf16 v[24:27], v[68:71], v[104:107], v[24:27]
	v_mfma_f32_16x16x32_bf16 v[28:31], v[68:71], v[108:111], v[28:31]
	ds_read_b128 v[120:123], v141 offset:4096
	s_waitcnt lgkmcnt(5)
	v_mfma_f32_16x16x32_bf16 v[32:35], v[72:75], v[96:99], v[32:35]
	v_mfma_f32_16x16x32_bf16 v[36:39], v[72:75], v[100:103], v[36:39]
	ds_read_b128 v[124:127], v141 offset:6144
	v_mfma_f32_16x16x32_bf16 v[40:43], v[72:75], v[104:107], v[40:43]
	v_mfma_f32_16x16x32_bf16 v[44:47], v[72:75], v[108:111], v[44:47]
	ds_read_b128 v[84:87], v137 offset:2048
	s_waitcnt lgkmcnt(6)
	v_mfma_f32_16x16x32_bf16 v[48:51], v[76:79], v[96:99], v[48:51]
	v_mfma_f32_16x16x32_bf16 v[52:55], v[76:79], v[100:103], v[52:55]
	ds_read_b128 v[88:91], v137 offset:4096
	v_mfma_f32_16x16x32_bf16 v[56:59], v[76:79], v[104:107], v[56:59]
	v_mfma_f32_16x16x32_bf16 v[60:63], v[76:79], v[108:111], v[60:63]
	ds_read_b128 v[92:95], v137 offset:6144
	s_waitcnt lgkmcnt(3)
	v_mfma_f32_16x16x32_bf16 v[0:3], v[80:83], v[112:115], v[0:3]
	v_mfma_f32_16x16x32_bf16 v[4:7], v[80:83], v[116:119], v[4:7]
	v_mfma_f32_16x16x32_bf16 v[8:11], v[80:83], v[120:123], v[8:11]
	v_mfma_f32_16x16x32_bf16 v[12:15], v[80:83], v[124:127], v[12:15]
	s_waitcnt lgkmcnt(2)
	v_mfma_f32_16x16x32_bf16 v[16:19], v[84:87], v[112:115], v[16:19]
	v_mfma_f32_16x16x32_bf16 v[20:23], v[84:87], v[116:119], v[20:23]
	v_mfma_f32_16x16x32_bf16 v[24:27], v[84:87], v[120:123], v[24:27]
	v_mfma_f32_16x16x32_bf16 v[28:31], v[84:87], v[124:127], v[28:31]
	s_waitcnt lgkmcnt(1)
	v_mfma_f32_16x16x32_bf16 v[32:35], v[88:91], v[112:115], v[32:35]
	v_mfma_f32_16x16x32_bf16 v[36:39], v[88:91], v[116:119], v[36:39]
	v_mfma_f32_16x16x32_bf16 v[40:43], v[88:91], v[120:123], v[40:43]
	v_mfma_f32_16x16x32_bf16 v[44:47], v[88:91], v[124:127], v[44:47]
	s_waitcnt lgkmcnt(0)
	v_mfma_f32_16x16x32_bf16 v[48:51], v[92:95], v[112:115], v[48:51]
	v_mfma_f32_16x16x32_bf16 v[52:55], v[92:95], v[116:119], v[52:55]
	v_mfma_f32_16x16x32_bf16 v[56:59], v[92:95], v[120:123], v[56:59]
	v_mfma_f32_16x16x32_bf16 v[60:63], v[92:95], v[124:127], v[60:63]
	s_waitcnt vmcnt(0)
	s_barrier
	s_add_i32 s99, s99, 1
	s_cmp_eq_u32 s99, 16
	s_movk_i32 s0, 0x80
	s_cselect_b32 s0, 0xfffff880, s0
	s_cselect_b32 s99, 0, s99
	s_ashr_i32 s1, s0, 31
	s_add_u32 s26, s26, s0
	s_addc_u32 s27, s27, s1
	s_add_u32 s28, s28, s0
	s_addc_u32 s29, s29, s1
	s_mov_b32 m0, s5
	s_nop 0
	global_load_lds_dwordx4 v132, s[26:27] offset:0
	global_load_lds_dwordx4 v133, s[26:27] offset:1024
	global_load_lds_dwordx4 v134, s[26:27] offset:2048
	global_load_lds_dwordx4 v135, s[26:27] offset:3072
	s_mov_b32 m0, s6
	s_nop 0
	global_load_lds_dwordx4 v132, s[28:29] offset:0
	global_load_lds_dwordx4 v133, s[28:29] offset:1024
	global_load_lds_dwordx4 v134, s[28:29] offset:2048
	global_load_lds_dwordx4 v135, s[28:29] offset:3072
	ds_read_b128 v[64:67], v138 offset:0
	ds_read_b128 v[96:99], v142 offset:0
	ds_read_b128 v[100:103], v142 offset:2048
	ds_read_b128 v[104:107], v142 offset:4096
	ds_read_b128 v[108:111], v142 offset:6144
	ds_read_b128 v[68:71], v138 offset:2048
	ds_read_b128 v[72:75], v138 offset:4096
	ds_read_b128 v[76:79], v138 offset:6144
	s_waitcnt lgkmcnt(3)
	v_mfma_f32_16x16x32_bf16 v[0:3], v[64:67], v[96:99], v[0:3]
	v_mfma_f32_16x16x32_bf16 v[4:7], v[64:67], v[100:103], v[4:7]
	ds_read_b128 v[80:83], v139 offset:0
	v_mfma_f32_16x16x32_bf16 v[8:11], v[64:67], v[104:107], v[8:11]
	v_mfma_f32_16x16x32_bf16 v[12:15], v[64:67], v[108:111], v[12:15]
	ds_read_b128 v[112:115], v143 offset:0
	s_waitcnt lgkmcnt(4)
	v_mfma_f32_16x16x32_bf16 v[16:19], v[68:71], v[96:99], v[16:19]
	v_mfma_f32_16x16x32_bf16 v[20:23], v[68:71], v[100:103], v[20:23]
	ds_read_b128 v[116:119], v143 offset:2048
	v_mfma_f32_16x16x32_bf16 v[24:27], v[68:71], v[104:107], v[24:27]
	v_mfma_f32_16x16x32_bf16 v[28:31], v[68:71], v[108:111], v[28:31]
	ds_read_b128 v[120:123], v143 offset:4096
	s_waitcnt lgkmcnt(5)
	v_mfma_f32_16x16x32_bf16 v[32:35], v[72:75], v[96:99], v[32:35]
	v_mfma_f32_16x16x32_bf16 v[36:39], v[72:75], v[100:103], v[36:39]
	ds_read_b128 v[124:127], v143 offset:6144
	v_mfma_f32_16x16x32_bf16 v[40:43], v[72:75], v[104:107], v[40:43]
	v_mfma_f32_16x16x32_bf16 v[44:47], v[72:75], v[108:111], v[44:47]
	ds_read_b128 v[84:87], v139 offset:2048
	s_waitcnt lgkmcnt(6)
	v_mfma_f32_16x16x32_bf16 v[48:51], v[76:79], v[96:99], v[48:51]
	v_mfma_f32_16x16x32_bf16 v[52:55], v[76:79], v[100:103], v[52:55]
	ds_read_b128 v[88:91], v139 offset:4096
	v_mfma_f32_16x16x32_bf16 v[56:59], v[76:79], v[104:107], v[56:59]
	v_mfma_f32_16x16x32_bf16 v[60:63], v[76:79], v[108:111], v[60:63]
	ds_read_b128 v[92:95], v139 offset:6144
	s_waitcnt lgkmcnt(3)
	v_mfma_f32_16x16x32_bf16 v[0:3], v[80:83], v[112:115], v[0:3]
	v_mfma_f32_16x16x32_bf16 v[4:7], v[80:83], v[116:119], v[4:7]
	v_mfma_f32_16x16x32_bf16 v[8:11], v[80:83], v[120:123], v[8:11]
	v_mfma_f32_16x16x32_bf16 v[12:15], v[80:83], v[124:127], v[12:15]
	s_waitcnt lgkmcnt(2)
	v_mfma_f32_16x16x32_bf16 v[16:19], v[84:87], v[112:115], v[16:19]
	v_mfma_f32_16x16x32_bf16 v[20:23], v[84:87], v[116:119], v[20:23]
	v_mfma_f32_16x16x32_bf16 v[24:27], v[84:87], v[120:123], v[24:27]
	v_mfma_f32_16x16x32_bf16 v[28:31], v[84:87], v[124:127], v[28:31]
	s_waitcnt lgkmcnt(1)
	v_mfma_f32_16x16x32_bf16 v[32:35], v[88:91], v[112:115], v[32:35]
	v_mfma_f32_16x16x32_bf16 v[36:39], v[88:91], v[116:119], v[36:39]
	v_mfma_f32_16x16x32_bf16 v[40:43], v[88:91], v[120:123], v[40:43]
	v_mfma_f32_16x16x32_bf16 v[44:47], v[88:91], v[124:127], v[44:47]
	s_waitcnt lgkmcnt(0)
	v_mfma_f32_16x16x32_bf16 v[48:51], v[92:95], v[112:115], v[48:51]
	v_mfma_f32_16x16x32_bf16 v[52:55], v[92:95], v[116:119], v[52:55]
	v_mfma_f32_16x16x32_bf16 v[56:59], v[92:95], v[120:123], v[56:59]
	v_mfma_f32_16x16x32_bf16 v[60:63], v[92:95], v[124:127], v[60:63]
	s_waitcnt vmcnt(0)
	s_barrier
	s_add_i32 s99, s99, 1
	s_cmp_eq_u32 s99, 16
	s_movk_i32 s0, 0x80
	s_cselect_b32 s0, 0xfffff880, s0
	s_cselect_b32 s99, 0, s99
	s_ashr_i32 s1, s0, 31
	s_add_u32 s26, s26, s0
	s_addc_u32 s27, s27, s1
	s_add_u32 s28, s28, s0
	s_addc_u32 s29, s29, s1
	s_mov_b32 m0, s7
	s_nop 0
	global_load_lds_dwordx4 v132, s[26:27] offset:0
	global_load_lds_dwordx4 v133, s[26:27] offset:1024
	global_load_lds_dwordx4 v134, s[26:27] offset:2048
	global_load_lds_dwordx4 v135, s[26:27] offset:3072
	s_mov_b32 m0, s8
	s_nop 0
	global_load_lds_dwordx4 v132, s[28:29] offset:0
	global_load_lds_dwordx4 v133, s[28:29] offset:1024
	global_load_lds_dwordx4 v134, s[28:29] offset:2048
	global_load_lds_dwordx4 v135, s[28:29] offset:3072
	ds_read_b128 v[64:67], v136 offset:0
	ds_read_b128 v[96:99], v140 offset:0
	ds_read_b128 v[100:103], v140 offset:2048
	ds_read_b128 v[104:107], v140 offset:4096
	ds_read_b128 v[108:111], v140 offset:6144
	ds_read_b128 v[68:71], v136 offset:2048
	ds_read_b128 v[72:75], v136 offset:4096
	ds_read_b128 v[76:79], v136 offset:6144
	s_waitcnt lgkmcnt(3)
	v_mfma_f32_16x16x32_bf16 v[0:3], v[64:67], v[96:99], v[0:3]
	v_mfma_f32_16x16x32_bf16 v[4:7], v[64:67], v[100:103], v[4:7]
	ds_read_b128 v[80:83], v137 offset:0
	v_mfma_f32_16x16x32_bf16 v[8:11], v[64:67], v[104:107], v[8:11]
	v_mfma_f32_16x16x32_bf16 v[12:15], v[64:67], v[108:111], v[12:15]
	ds_read_b128 v[112:115], v141 offset:0
	s_waitcnt lgkmcnt(4)
	v_mfma_f32_16x16x32_bf16 v[16:19], v[68:71], v[96:99], v[16:19]
	v_mfma_f32_16x16x32_bf16 v[20:23], v[68:71], v[100:103], v[20:23]
	ds_read_b128 v[116:119], v141 offset:2048
	v_mfma_f32_16x16x32_bf16 v[24:27], v[68:71], v[104:107], v[24:27]
	v_mfma_f32_16x16x32_bf16 v[28:31], v[68:71], v[108:111], v[28:31]
	ds_read_b128 v[120:123], v141 offset:4096
	s_waitcnt lgkmcnt(5)
	v_mfma_f32_16x16x32_bf16 v[32:35], v[72:75], v[96:99], v[32:35]
	v_mfma_f32_16x16x32_bf16 v[36:39], v[72:75], v[100:103], v[36:39]
	ds_read_b128 v[124:127], v141 offset:6144
	v_mfma_f32_16x16x32_bf16 v[40:43], v[72:75], v[104:107], v[40:43]
	v_mfma_f32_16x16x32_bf16 v[44:47], v[72:75], v[108:111], v[44:47]
	ds_read_b128 v[84:87], v137 offset:2048
	s_waitcnt lgkmcnt(6)
	v_mfma_f32_16x16x32_bf16 v[48:51], v[76:79], v[96:99], v[48:51]
	v_mfma_f32_16x16x32_bf16 v[52:55], v[76:79], v[100:103], v[52:55]
	ds_read_b128 v[88:91], v137 offset:4096
	v_mfma_f32_16x16x32_bf16 v[56:59], v[76:79], v[104:107], v[56:59]
	v_mfma_f32_16x16x32_bf16 v[60:63], v[76:79], v[108:111], v[60:63]
	ds_read_b128 v[92:95], v137 offset:6144
	s_waitcnt lgkmcnt(3)
	v_mfma_f32_16x16x32_bf16 v[0:3], v[80:83], v[112:115], v[0:3]
	v_mfma_f32_16x16x32_bf16 v[4:7], v[80:83], v[116:119], v[4:7]
	v_mfma_f32_16x16x32_bf16 v[8:11], v[80:83], v[120:123], v[8:11]
	v_mfma_f32_16x16x32_bf16 v[12:15], v[80:83], v[124:127], v[12:15]
	s_waitcnt lgkmcnt(2)
	v_mfma_f32_16x16x32_bf16 v[16:19], v[84:87], v[112:115], v[16:19]
	v_mfma_f32_16x16x32_bf16 v[20:23], v[84:87], v[116:119], v[20:23]
	v_mfma_f32_16x16x32_bf16 v[24:27], v[84:87], v[120:123], v[24:27]
	v_mfma_f32_16x16x32_bf16 v[28:31], v[84:87], v[124:127], v[28:31]
	s_waitcnt lgkmcnt(1)
	v_mfma_f32_16x16x32_bf16 v[32:35], v[88:91], v[112:115], v[32:35]
	v_mfma_f32_16x16x32_bf16 v[36:39], v[88:91], v[116:119], v[36:39]
	v_mfma_f32_16x16x32_bf16 v[40:43], v[88:91], v[120:123], v[40:43]
	v_mfma_f32_16x16x32_bf16 v[44:47], v[88:91], v[124:127], v[44:47]
	s_waitcnt lgkmcnt(0)
	v_mfma_f32_16x16x32_bf16 v[48:51], v[92:95], v[112:115], v[48:51]
	v_mfma_f32_16x16x32_bf16 v[52:55], v[92:95], v[116:119], v[52:55]
	v_mfma_f32_16x16x32_bf16 v[56:59], v[92:95], v[120:123], v[56:59]
	v_mfma_f32_16x16x32_bf16 v[60:63], v[92:95], v[124:127], v[60:63]
	s_waitcnt vmcnt(0)
	s_barrier
	ds_read_b128 v[64:67], v138 offset:0
	ds_read_b128 v[96:99], v142 offset:0
	ds_read_b128 v[100:103], v142 offset:2048
	ds_read_b128 v[104:107], v142 offset:4096
	ds_read_b128 v[108:111], v142 offset:6144
	ds_read_b128 v[68:71], v138 offset:2048
	ds_read_b128 v[72:75], v138 offset:4096
	ds_read_b128 v[76:79], v138 offset:6144
	s_waitcnt lgkmcnt(3)
	v_mfma_f32_16x16x32_bf16 v[0:3], v[64:67], v[96:99], v[0:3]
	v_mfma_f32_16x16x32_bf16 v[4:7], v[64:67], v[100:103], v[4:7]
	ds_read_b128 v[80:83], v139 offset:0
	v_mfma_f32_16x16x32_bf16 v[8:11], v[64:67], v[104:107], v[8:11]
	v_mfma_f32_16x16x32_bf16 v[12:15], v[64:67], v[108:111], v[12:15]
	ds_read_b128 v[112:115], v143 offset:0
	s_waitcnt lgkmcnt(4)
	v_mfma_f32_16x16x32_bf16 v[16:19], v[68:71], v[96:99], v[16:19]
	v_mfma_f32_16x16x32_bf16 v[20:23], v[68:71], v[100:103], v[20:23]
	ds_read_b128 v[116:119], v143 offset:2048
	v_mfma_f32_16x16x32_bf16 v[24:27], v[68:71], v[104:107], v[24:27]
	v_mfma_f32_16x16x32_bf16 v[28:31], v[68:71], v[108:111], v[28:31]
	ds_read_b128 v[120:123], v143 offset:4096
	s_waitcnt lgkmcnt(5)
	v_mfma_f32_16x16x32_bf16 v[32:35], v[72:75], v[96:99], v[32:35]
	v_mfma_f32_16x16x32_bf16 v[36:39], v[72:75], v[100:103], v[36:39]
	ds_read_b128 v[124:127], v143 offset:6144
	v_mfma_f32_16x16x32_bf16 v[40:43], v[72:75], v[104:107], v[40:43]
	v_mfma_f32_16x16x32_bf16 v[44:47], v[72:75], v[108:111], v[44:47]
	ds_read_b128 v[84:87], v139 offset:2048
	s_waitcnt lgkmcnt(6)
	v_mfma_f32_16x16x32_bf16 v[48:51], v[76:79], v[96:99], v[48:51]
	v_mfma_f32_16x16x32_bf16 v[52:55], v[76:79], v[100:103], v[52:55]
	ds_read_b128 v[88:91], v139 offset:4096
	v_mfma_f32_16x16x32_bf16 v[56:59], v[76:79], v[104:107], v[56:59]
	v_mfma_f32_16x16x32_bf16 v[60:63], v[76:79], v[108:111], v[60:63]
	ds_read_b128 v[92:95], v139 offset:6144
	s_waitcnt lgkmcnt(3)
	v_mfma_f32_16x16x32_bf16 v[0:3], v[80:83], v[112:115], v[0:3]
	v_mfma_f32_16x16x32_bf16 v[4:7], v[80:83], v[116:119], v[4:7]
	v_mfma_f32_16x16x32_bf16 v[8:11], v[80:83], v[120:123], v[8:11]
	v_mfma_f32_16x16x32_bf16 v[12:15], v[80:83], v[124:127], v[12:15]
	s_waitcnt lgkmcnt(2)
	v_mfma_f32_16x16x32_bf16 v[16:19], v[84:87], v[112:115], v[16:19]
	v_mfma_f32_16x16x32_bf16 v[20:23], v[84:87], v[116:119], v[20:23]
	v_mfma_f32_16x16x32_bf16 v[24:27], v[84:87], v[120:123], v[24:27]
	v_mfma_f32_16x16x32_bf16 v[28:31], v[84:87], v[124:127], v[28:31]
	s_waitcnt lgkmcnt(1)
	v_mfma_f32_16x16x32_bf16 v[32:35], v[88:91], v[112:115], v[32:35]
	v_mfma_f32_16x16x32_bf16 v[36:39], v[88:91], v[116:119], v[36:39]
	v_mfma_f32_16x16x32_bf16 v[40:43], v[88:91], v[120:123], v[40:43]
	v_mfma_f32_16x16x32_bf16 v[44:47], v[88:91], v[124:127], v[44:47]
	s_waitcnt lgkmcnt(0)
	v_mfma_f32_16x16x32_bf16 v[48:51], v[92:95], v[112:115], v[48:51]
	v_mfma_f32_16x16x32_bf16 v[52:55], v[92:95], v[116:119], v[52:55]
	v_mfma_f32_16x16x32_bf16 v[56:59], v[92:95], v[120:123], v[56:59]
	v_mfma_f32_16x16x32_bf16 v[60:63], v[92:95], v[124:127], v[60:63]
	v_readlane_b32 s38, v255, 35
	s_add_i32 s38, s25, s38
	s_cmpk_lt_u32 s38, 0x1280
	s_cbranch_scc0 .Lgin_nonext
	s_and_b32 s0, s38, 63
	s_lshr_b32 s1, s38, 6
	s_mul_i32 s4, s70, 0x1280000
	s_lshl_b32 s39, s1, 18
	s_add_u32 s4, s4, s39
	s_add_u32 s26, s96, s4
	s_addc_u32 s27, s97, 0
	s_lshl_b32 s4, s0, 18
	s_add_u32 s4, s4, 0x82a6100
	s_add_u32 s28, s96, s4
	s_addc_u32 s29, s97, 0
	s_lshl_b32 s0, s98, 7
	s_add_u32 s26, s26, s0
	s_addc_u32 s27, s27, 0
	s_add_u32 s28, s28, s0
	s_addc_u32 s29, s29, 0
	s_mov_b32 s99, s98
	s_mov_b32 m0, s5
	s_nop 0
	global_load_lds_dwordx4 v132, s[26:27] offset:0
	global_load_lds_dwordx4 v133, s[26:27] offset:1024
	global_load_lds_dwordx4 v134, s[26:27] offset:2048
	global_load_lds_dwordx4 v135, s[26:27] offset:3072
	s_mov_b32 m0, s6
	s_nop 0
	global_load_lds_dwordx4 v132, s[28:29] offset:0
	global_load_lds_dwordx4 v133, s[28:29] offset:1024
	global_load_lds_dwordx4 v134, s[28:29] offset:2048
	global_load_lds_dwordx4 v135, s[28:29] offset:3072
